# CMP2 importance quad reductions via DPP quad_perm instead of ds_bpermute (with recounted lgkmcnt waits), on top of previous stack
# baseline (speedup 1.0000x reference)
; #define LAS __attribute__((address_space(3)))
; DI int tid_of(int wv) { int ln; asm volatile("v_mbcnt_lo_u32_b32 %0, -1, 0\n\tv_mbcnt_hi_u32_b32 %0, -1, %0" : "=v"(ln)); return wv * 64 + ln; }
; DI float shx(float v, int m, int lane) { return __builtin_bit_cast(float, __builtin_amdgcn_ds_bpermute((lane ^ m) << 2, __builtin_bit_cast(int, v))); }
; DI void load_q(bf16x8 (&q)[8], const bf16* qrow, int h, const float* gain, int lane) {
;     float ss = 0.f;
; #pragma unroll
;     for (int s = 0; s < 8; ++s) { const u32x4 raw = *(const u32x4*)(qrow + 16 * s + 8 * h);
; #pragma unroll
;         for (int j = 0; j < 4; ++j) { const float a = __builtin_bit_cast(float, raw[j] << 16), b = __builtin_bit_cast(float, raw[j] & 0xffff0000u); ss += a * a + b * b; } }
;     ss += shx(ss, 32, lane);
; DI void nsa_unit(const P& p, ldsp lds, int u, int l, int wv) {
;     const int tid = tid_of(wv), lane = tid & 63, w = tid >> 6, r32 = lane & 31, h = lane >> 5;
;     const int qb = 127 - (u >> 2), bg = u & 3, b = bg >> 1, g = bg & 1;
;     const bf16* heads = (const bf16*)(p.ws + WS_HEADS); const bf16* VT = (const bf16*)(p.ws + WS_VT);
;     const int ql = r32 >> 2, r = r32 & 3, qi = w * 8 + ql, t = qb * 64 + qi, hn = g * 4 + r;
; #pragma unroll
;     for (int k = 0; k < 8; ++k) *(LAS f32x4*)(lds + A_IMPG + (k * 512 + tid) * 16) = (f32x4){0.f, 0.f, 0.f, 0.f};
;     bf16x8 q[8]; load_q(q, heads + ((size_t)(16 + hn) * M + b * T + t) * HD, h, p.nqn + l * HD, lane);
.Lnsa_prio_skip:
	v_mbcnt_lo_u32_b32 v200, -1, 0
	v_mbcnt_hi_u32_b32 v200, -1, v200
	s_and_b64 vcc, s[8:9], exec
	v_and_b32_e32 v159, 3, v200
	v_add_u32_e32 v168, s3, v200
	v_ashrrev_i32_e32 v166, 6, v168
	s_cselect_b32 s3, 4, 0
	v_bfe_u32 v198, v200, 2, 3
	v_lshlrev_b32_e32 v199, 3, v166
	v_or_b32_e32 v196, s3, v159
	s_lshl_b32 s3, s30, 13
	v_or_b32_e32 v147, v199, v198
	s_and_b32 s3, s3, 0x2000
	v_add_u32_e32 v148, s1, v147
	v_lshl_or_b32 v0, v196, 14, s3
	v_or_b32_e32 v0, 0x40000, v0
	v_ashrrev_i32_e32 v149, 31, v148
	v_lshl_add_u64 v[2:3], v[0:1], 0, v[148:149]
	v_readlane_b32 s4, v253, 10
	v_bfe_u32 v201, v200, 5, 1
	v_lshlrev_b64 v[2:3], 8, v[2:3]
	v_readlane_b32 s5, v253, 11
	v_lshlrev_b32_e32 v156, 4, v201
	v_mov_b32_e32 v157, v1
	v_lshl_add_u64 v[2:3], s[4:5], 0, v[2:3]
	v_lshl_add_u64 v[110:111], v[2:3], 0, v[156:157]
	global_load_dwordx4 v[6:9], v[110:111], off
	global_load_dwordx4 v[10:13], v[110:111], off offset:32
	global_load_dwordx4 v[14:17], v[110:111], off offset:64
	global_load_dwordx4 v[2:5], v[110:111], off offset:96
	s_mov_b32 s18, s17
	s_mov_b32 s19, s17
	v_lshlrev_b32_e32 v157, 4, v168
	s_mov_b32 s16, s17
	v_mov_b64_e32 v[20:21], s[18:19]
	v_add_u32_e32 v0, 0, v157
	v_mov_b64_e32 v[18:19], s[16:17]
	v_add_u32_e32 v0, 0x11a00, v0
	ds_write_b128 v0, v[18:21]
	ds_write_b128 v0, v[18:21] offset:8192
	ds_write_b128 v0, v[18:21] offset:16384
	ds_write_b128 v0, v[18:21] offset:24576
	ds_write_b128 v0, v[18:21] offset:32768
	ds_write_b128 v0, v[18:21] offset:40960
	ds_write_b128 v0, v[18:21] offset:49152
	ds_write_b128 v0, v[18:21] offset:57344
	global_load_dwordx4 v[34:37], v[110:111], off offset:128
	global_load_dwordx4 v[38:41], v[110:111], off offset:160
	v_writelane_b32 v255, s3, 20
	global_load_dwordx4 v[106:109], v[110:111], off offset:192
	global_load_dwordx4 v[112:115], v[110:111], off offset:224
	v_readlane_b32 s4, v255, 13
	v_readlane_b32 s5, v255, 14
	v_and_b32_e32 v167, 63, v200
	v_lshlrev_b32_e32 v169, 2, v167
	v_xor_b32_e32 v197, 0x80, v169
	v_mov_b32_e32 v190, 0
	v_xor_b32_e32 v170, 4, v169
	v_xor_b32_e32 v171, 8, v169
	v_mov_b32_e32 v154, 0
	s_waitcnt vmcnt(0)
	v_lshlrev_b32_e32 v0, 16, v6
	v_and_b32_e32 v6, 0xffff0000, v6
	v_lshlrev_b32_e32 v18, 16, v7
	v_and_b32_e32 v7, 0xffff0000, v7
	v_lshlrev_b32_e32 v19, 16, v8
	v_and_b32_e32 v8, 0xffff0000, v8
	v_mul_f32_e32 v6, v6, v6
	v_mul_f32_e32 v7, v7, v7
	v_lshlrev_b32_e32 v20, 16, v9
	v_and_b32_e32 v9, 0xffff0000, v9
	v_mul_f32_e32 v8, v8, v8
	v_fmac_f32_e32 v6, v0, v0
	v_fmac_f32_e32 v7, v18, v18
	v_lshlrev_b32_e32 v21, 16, v10
	v_and_b32_e32 v10, 0xffff0000, v10
	v_mul_f32_e32 v9, v9, v9
	v_fmac_f32_e32 v8, v19, v19
	v_add_f32_e32 v0, v6, v7
	v_lshlrev_b32_e32 v22, 16, v11
	v_and_b32_e32 v11, 0xffff0000, v11
	v_mul_f32_e32 v10, v10, v10
	v_fmac_f32_e32 v9, v20, v20
	v_add_f32_e32 v0, v8, v0
	v_lshlrev_b32_e32 v23, 16, v12
	v_and_b32_e32 v12, 0xffff0000, v12
	v_mul_f32_e32 v11, v11, v11
	v_fmac_f32_e32 v10, v21, v21
	v_add_f32_e32 v0, v9, v0
	v_lshlrev_b32_e32 v24, 16, v13
	v_and_b32_e32 v13, 0xffff0000, v13
	v_mul_f32_e32 v12, v12, v12
	v_fmac_f32_e32 v11, v22, v22
	v_add_f32_e32 v0, v10, v0
	v_lshlrev_b32_e32 v25, 16, v14
	v_and_b32_e32 v14, 0xffff0000, v14
	v_mul_f32_e32 v13, v13, v13
	v_fmac_f32_e32 v12, v23, v23
	v_add_f32_e32 v0, v11, v0
	v_lshlrev_b32_e32 v26, 16, v15
	v_and_b32_e32 v15, 0xffff0000, v15
	v_mul_f32_e32 v14, v14, v14
	v_fmac_f32_e32 v13, v24, v24
	v_add_f32_e32 v0, v12, v0
	v_lshlrev_b32_e32 v27, 16, v16
	v_and_b32_e32 v16, 0xffff0000, v16
	v_mul_f32_e32 v15, v15, v15
	v_fmac_f32_e32 v14, v25, v25
	v_add_f32_e32 v0, v13, v0
	v_lshlrev_b32_e32 v28, 16, v17
	v_and_b32_e32 v17, 0xffff0000, v17
	v_mul_f32_e32 v16, v16, v16
	v_fmac_f32_e32 v15, v26, v26
	v_add_f32_e32 v0, v14, v0
	v_fmac_f32_e32 v16, v27, v27
	v_add_f32_e32 v0, v15, v0
	v_mul_f32_e32 v6, v17, v17
	v_add_f32_e32 v0, v16, v0
	v_fmac_f32_e32 v6, v28, v28
	v_add_f32_e32 v0, v6, v0
	v_lshlrev_b32_e32 v6, 16, v2
	v_and_b32_e32 v2, 0xffff0000, v2
	v_mul_f32_e32 v2, v2, v2
	v_fmac_f32_e32 v2, v6, v6
	v_add_f32_e32 v0, v2, v0
	v_lshlrev_b32_e32 v2, 16, v3
	v_and_b32_e32 v3, 0xffff0000, v3
	v_mul_f32_e32 v3, v3, v3
	v_fmac_f32_e32 v3, v2, v2
	v_add_f32_e32 v0, v3, v0
	v_and_b32_e32 v3, 0xffff0000, v4
	v_lshlrev_b32_e32 v2, 16, v4
	v_mul_f32_e32 v3, v3, v3
	v_fmac_f32_e32 v3, v2, v2
	v_add_f32_e32 v0, v3, v0
	v_and_b32_e32 v3, 0xffff0000, v5
	v_lshlrev_b32_e32 v2, 16, v5
	v_mul_f32_e32 v3, v3, v3
	v_fmac_f32_e32 v3, v2, v2
	v_and_b32_e32 v10, 32, v200
	v_add_f32_e32 v0, v3, v0
	global_load_dwordx4 v[94:97], v10, s[4:5] offset:16
	global_load_dwordx4 v[102:105], v10, s[4:5]
	global_load_dwordx4 v[98:101], v[110:111], off
	global_load_dwordx4 v[86:89], v[110:111], off offset:32
	global_load_dwordx4 v[82:85], v10, s[4:5] offset:80
	global_load_dwordx4 v[90:93], v10, s[4:5] offset:64
	global_load_dwordx4 v[70:73], v10, s[4:5] offset:144
	global_load_dwordx4 v[78:81], v10, s[4:5] offset:128
	global_load_dwordx4 v[74:77], v[110:111], off offset:64
	global_load_dwordx4 v[62:65], v[110:111], off offset:96
	global_load_dwordx4 v[58:61], v10, s[4:5] offset:208
	global_load_dwordx4 v[66:69], v10, s[4:5] offset:192
	global_load_dwordx4 v[46:49], v10, s[4:5] offset:272
	global_load_dwordx4 v[54:57], v10, s[4:5] offset:256
	global_load_dwordx4 v[50:53], v[110:111], off offset:128
	global_load_dwordx4 v[30:33], v[110:111], off offset:160
; DI float shx(float v, int m, int lane) { return __builtin_bit_cast(float, __builtin_amdgcn_ds_bpermute((lane ^ m) << 2, __builtin_bit_cast(int, v))); }
; DI void load_q(bf16x8 (&q)[8], const bf16* qrow, int h, const float* gain, int lane) {
;     ...
;     for (int s = 0; s < 8; ++s) { const u32x4 raw = *(const u32x4*)(qrow + 16 * s + 8 * h);
; #pragma unroll
;         for (int j = 0; j < 4; ++j) { const float a = __builtin_bit_cast(float, raw[j] << 16), b = __builtin_bit_cast(float, raw[j] & 0xffff0000u); ss += a * a + b * b; } }
;     ss += shx(ss, 32, lane);
;     const float rs = rsqrtf(ss * (1.0f / HD) + EPS) * C2;
; DI void nsa_unit(const P& p, ldsp lds, int u, int l, int wv) {
;     ...
;     if (g == 0) { const float* fq = p.nqn + l * HD; const float* fk = p.skn + l * HD; const float* fc = p.ckn + l * HD;
;       float gq = fmaxf(fabsf(fq[lane]), fabsf(fq[lane + 64])), gk = fmaxf(fmaxf(fabsf(fk[lane]), fabsf(fk[lane + 64])), fmaxf(fabsf(fc[lane]), fabsf(fc[lane + 64])));
; #pragma unroll
;       for (int o2 = 1; o2 < 64; o2 <<= 1) { gq = fmaxf(gq, shx(gq, o2, lane)); gk = fmaxf(gk, shx(gk, o2, lane)); }
;       c.bqk = 1.02f * C2 * 128.0f * gq * gk; }
	global_load_dwordx4 v[26:29], v10, s[4:5] offset:336
	global_load_dwordx4 v[42:45], v10, s[4:5] offset:320
	global_load_dwordx4 v[14:17], v10, s[4:5] offset:400
	global_load_dwordx4 v[22:25], v10, s[4:5] offset:384
	global_load_dwordx4 v[18:21], v[110:111], off offset:192
	global_load_dwordx4 v[6:9], v[110:111], off offset:224
	global_load_dwordx4 v[2:5], v10, s[4:5] offset:464
	s_nop 0
	global_load_dwordx4 v[10:13], v10, s[4:5] offset:448
	v_lshlrev_b32_e32 v110, 16, v34
	v_and_b32_e32 v34, 0xffff0000, v34
	v_mul_f32_e32 v34, v34, v34
	v_fmac_f32_e32 v34, v110, v110
	v_add_f32_e32 v0, v34, v0
	v_lshlrev_b32_e32 v34, 16, v35
	v_and_b32_e32 v35, 0xffff0000, v35
	v_mul_f32_e32 v35, v35, v35
	v_fmac_f32_e32 v35, v34, v34
	v_add_f32_e32 v0, v35, v0
	v_and_b32_e32 v35, 0xffff0000, v36
	v_lshlrev_b32_e32 v34, 16, v36
	v_mul_f32_e32 v35, v35, v35
	v_fmac_f32_e32 v35, v34, v34
	v_add_f32_e32 v0, v35, v0
	v_and_b32_e32 v35, 0xffff0000, v37
	v_lshlrev_b32_e32 v34, 16, v37
	v_mul_f32_e32 v35, v35, v35
	v_fmac_f32_e32 v35, v34, v34
	v_add_f32_e32 v0, v35, v0
	v_and_b32_e32 v35, 0xffff0000, v38
	v_lshlrev_b32_e32 v34, 16, v38
	v_mul_f32_e32 v35, v35, v35
	v_fmac_f32_e32 v35, v34, v34
	v_add_f32_e32 v0, v35, v0
	v_and_b32_e32 v35, 0xffff0000, v39
	v_lshlrev_b32_e32 v34, 16, v39
	v_mul_f32_e32 v35, v35, v35
	v_fmac_f32_e32 v35, v34, v34
	v_and_b32_e32 v37, 0xffff0000, v41
	v_and_b32_e32 v36, 0xffff0000, v40
	v_add_f32_e32 v0, v35, v0
	v_lshlrev_b32_e32 v35, 16, v41
	v_lshlrev_b32_e32 v34, 16, v40
	v_pk_mul_f32 v[36:37], v[36:37], v[36:37]
	s_nop 0
	v_pk_fma_f32 v[34:35], v[34:35], v[34:35], v[36:37]
	v_and_b32_e32 v37, 0xffff0000, v107
	v_add_f32_e32 v0, v34, v0
	v_and_b32_e32 v36, 0xffff0000, v106
	v_add_f32_e32 v0, v35, v0
	v_lshlrev_b32_e32 v35, 16, v107
	v_lshlrev_b32_e32 v34, 16, v106
	v_pk_mul_f32 v[36:37], v[36:37], v[36:37]
	s_nop 0
	v_pk_fma_f32 v[34:35], v[34:35], v[34:35], v[36:37]
	v_and_b32_e32 v37, 0xffff0000, v109
	v_add_f32_e32 v0, v34, v0
	v_and_b32_e32 v36, 0xffff0000, v108
	v_add_f32_e32 v0, v35, v0
	v_lshlrev_b32_e32 v35, 16, v109
	v_lshlrev_b32_e32 v34, 16, v108
	v_pk_mul_f32 v[36:37], v[36:37], v[36:37]
	s_nop 0
	v_pk_fma_f32 v[34:35], v[34:35], v[34:35], v[36:37]
	v_and_b32_e32 v37, 0xffff0000, v113
	v_add_f32_e32 v0, v34, v0
	v_and_b32_e32 v36, 0xffff0000, v112
	v_add_f32_e32 v0, v35, v0
	v_lshlrev_b32_e32 v35, 16, v113
	v_lshlrev_b32_e32 v34, 16, v112
	v_pk_mul_f32 v[36:37], v[36:37], v[36:37]
	s_nop 0
	v_pk_fma_f32 v[34:35], v[34:35], v[34:35], v[36:37]
	v_and_b32_e32 v37, 0xffff0000, v115
	v_add_f32_e32 v0, v34, v0
	v_and_b32_e32 v36, 0xffff0000, v114
	v_add_f32_e32 v0, v35, v0
	v_lshlrev_b32_e32 v35, 16, v115
	v_lshlrev_b32_e32 v34, 16, v114
	v_pk_mul_f32 v[36:37], v[36:37], v[36:37]
	s_nop 0
	v_pk_fma_f32 v[34:35], v[34:35], v[34:35], v[36:37]
	s_nop 0
	v_add_f32_e32 v0, v34, v0
	v_add_f32_e32 v0, v35, v0
	ds_bpermute_b32 v106, v197, v0
	s_cbranch_vccnz .LBB0_591
	v_readlane_b32 s4, v255, 13
	v_readlane_b32 s5, v255, 14
	s_nop 4
	global_load_dword v34, v169, s[4:5]
	global_load_dword v35, v169, s[4:5] offset:256
	v_readlane_b32 s4, v255, 15
	v_readlane_b32 s5, v255, 16
	s_waitcnt vmcnt(1)
	v_max_f32_e64 v34, |v34|, |v34|
	s_waitcnt vmcnt(0)
	v_max_f32_e64 v35, |v35|, |v35|
	v_max_f32_e32 v34, v34, v35
	global_load_dword v35, v169, s[4:5]
	global_load_dword v36, v169, s[4:5] offset:256
	v_readlane_b32 s4, v255, 17
	v_readlane_b32 s5, v255, 18
	s_nop 4
	global_load_dword v37, v169, s[4:5]
	global_load_dword v38, v169, s[4:5] offset:256
	s_waitcnt vmcnt(1)
	v_max_f32_e64 v37, |v37|, |v37|
	s_waitcnt vmcnt(0)
	v_max_f32_e64 v38, |v38|, |v38|
	v_max_f32_e32 v37, v37, v38
	v_max3_f32 v35, |v35|, |v36|, v37
	s_nop 1
	v_mov_b32_dpp v36, v34 quad_perm:[1,0,3,2] row_mask:0xf bank_mask:0xf
	s_waitcnt lgkmcnt(0)
	v_max_f32_e32 v36, v36, v36
	v_max_f32_e32 v34, v34, v36
	s_nop 1
	v_mov_b32_dpp v36, v35 quad_perm:[1,0,3,2] row_mask:0xf bank_mask:0xf
	s_waitcnt lgkmcnt(0)
	v_max_f32_e32 v36, v36, v36
	v_max_f32_e32 v35, v35, v36
	s_nop 1
	v_mov_b32_dpp v36, v34 quad_perm:[2,3,0,1] row_mask:0xf bank_mask:0xf
	s_waitcnt lgkmcnt(0)
	v_max_f32_e32 v36, v36, v36
	v_max_f32_e32 v34, v34, v36
	s_nop 1
	v_mov_b32_dpp v36, v35 quad_perm:[2,3,0,1] row_mask:0xf bank_mask:0xf
	s_waitcnt lgkmcnt(0)
	v_max_f32_e32 v36, v36, v36
	v_max_f32_e32 v35, v35, v36
	v_xor_b32_e32 v36, 16, v169
	ds_bpermute_b32 v37, v36, v34
	ds_bpermute_b32 v36, v36, v35
	s_waitcnt lgkmcnt(1)
	v_max_f32_e32 v37, v37, v37
	s_waitcnt lgkmcnt(0)
	v_max_f32_e32 v36, v36, v36
	v_max_f32_e32 v34, v34, v37
	v_max_f32_e32 v35, v35, v36
	v_xor_b32_e32 v36, 32, v169
	ds_bpermute_b32 v37, v36, v34
	ds_bpermute_b32 v36, v36, v35
	s_waitcnt lgkmcnt(1)
	v_max_f32_e32 v37, v37, v37
	s_waitcnt lgkmcnt(0)
	v_max_f32_e32 v36, v36, v36
	v_max_f32_e32 v34, v34, v37
	v_max_f32_e32 v35, v35, v36
	v_xor_b32_e32 v36, 64, v169
	ds_bpermute_b32 v37, v36, v34
	ds_bpermute_b32 v36, v36, v35
	s_waitcnt lgkmcnt(1)
	v_max_f32_e32 v37, v37, v37
	v_max_f32_e32 v34, v34, v37
	s_waitcnt lgkmcnt(0)
	v_max_f32_e32 v36, v36, v36
	v_max_f32_e32 v35, v35, v36
	ds_bpermute_b32 v36, v197, v34
	s_waitcnt lgkmcnt(0)
	v_max_f32_e32 v36, v36, v36
	v_max_f32_e32 v34, v34, v36
	ds_bpermute_b32 v36, v197, v35
	v_mul_f32_e32 v34, 0x4185307d, v34
	s_waitcnt lgkmcnt(0)
	v_max_f32_e32 v36, v36, v36
	v_max_f32_e32 v35, v35, v36
	v_mul_f32_e32 v154, v35, v34

; #define LAS __attribute__((address_space(3)))
; DI float shx(float v, int m, int lane) { return __builtin_bit_cast(float, __builtin_amdgcn_ds_bpermute((lane ^ m) << 2, __builtin_bit_cast(int, v))); }
; DI float fexp2(float x) { return __builtin_amdgcn_exp2f(x); }
; #define MFMA32(a, b, c) __builtin_amdgcn_mfma_f32_32x32x16_bf16((a), (b), (c), 0, 0, 0)
; template <int MODE> DI void attn_h1(AttnCtx& c, const bf16x8 (&q)[8], f32x16 (&o)[4], f32x16& s0, f32x16& s1, ldsp lds, int kbuf, int bbuf, int tj, int lane) {
;     ...
;             ldsp kl = lds + kbuf + r32 * KPITCH + h * 16;
; #pragma unroll
;             for (int e = 0; e < 16; ++e) { s0[e] = 0.f; s1[e] = 0.f; }
; #pragma unroll
;             for (int s = 0; s < 8; ++s) {
;                 const bf16x8 ka = *(const LAS bf16x8*)(kl + s * 32), kb = *(const LAS bf16x8*)(kl + 32 * KPITCH + s * 32);
;                 s0 = MFMA32(ka, q[s], s0); s1 = MFMA32(kb, q[s], s1);
; template <int MODE> DI void attn_h2(AttnCtx& c, f32x16 (&o)[4], f32x16& s0, f32x16& s1, ldsp lds, int vbuf, int tj, int lane) {
;     ...
;             if (MODE == MD_CMP2) {
; #pragma unroll
;                 for (int e = 0; e < 16; ++e) { s0[e] = fexp2(s0[e] - c.m) * c.l; s1[e] = fexp2(s1[e] - c.m) * c.l; }
;                 LAS float* impg = (LAS float*)(lds + A_IMPG) + c.qi * 128; LAS float* imp3 = (LAS float*)(lds + A_IMP3) + c.qi * 128;
; #pragma unroll
;                 for (int kb = 0; kb < 2; ++kb)
; #pragma unroll
;                     for (int g4 = 0; g4 < 4; ++g4) {
;                         float G, p3;
;                         if (kb == 0) { G = (s0[4 * g4] + s0[4 * g4 + 1]) + (s0[4 * g4 + 2] + s0[4 * g4 + 3]); p3 = s0[4 * g4 + 3]; }
;                         else { G = (s1[4 * g4] + s1[4 * g4 + 1]) + (s1[4 * g4 + 2] + s1[4 * g4 + 3]); p3 = s1[4 * g4 + 3]; }
;                         G += shx(G, 1, lane); G += shx(G, 2, lane); p3 += shx(p3, 1, lane); p3 += shx(p3, 2, lane);
;                         const int n4 = tj * 16 + kb * 8 + 2 * g4 + h;
;                         if ((lane & 3) == 0) { impg[n4] = G; if (n4 + 1 < 128) imp3[n4 + 1] = p3; }
;                     }
.LBB0_625:
	ds_read_b128 v[2:5], v205
	ds_read_b128 v[64:67], v205 offset:32
	v_add_f32_e32 v59, v62, v59
	v_div_scale_f32 v76, s[18:19], v59, v59, 1.0
	s_waitcnt lgkmcnt(1)
	v_mfma_f32_32x32x16_bf16 v[18:33], v[2:5], v[98:101], 0
	ds_read_b128 v[2:5], v205 offset:8704
	ds_read_b128 v[68:71], v205 offset:8736
	v_rcp_f32_e32 v77, v76
	v_div_scale_f32 v78, vcc, 1.0, v59, 1.0
	s_add_i32 s19, 0, 0x11a00
	v_cmp_eq_u32_e64 s[46:47], 0, v159
	s_waitcnt lgkmcnt(1)
	v_mfma_f32_32x32x16_bf16 v[2:17], v[2:5], v[98:101], 0
	v_mfma_f32_32x32x16_bf16 v[18:33], v[64:67], v[102:105], v[18:33]
	s_waitcnt lgkmcnt(0)
	v_mfma_f32_32x32x16_bf16 v[2:17], v[68:71], v[102:105], v[2:17]
	ds_read_b128 v[64:67], v205 offset:64
	ds_read_b128 v[68:71], v205 offset:96
	s_waitcnt lgkmcnt(1)
	v_mfma_f32_32x32x16_bf16 v[18:33], v[64:67], v[106:109], v[18:33]
	ds_read_b128 v[64:67], v205 offset:8768
	ds_read_b128 v[72:75], v205 offset:8800
	s_waitcnt lgkmcnt(2)
	v_mfma_f32_32x32x16_bf16 v[18:33], v[68:71], v[110:113], v[18:33]
	ds_read_b128 v[68:71], v205 offset:128
	ds_read_b128 v[86:89], v205 offset:160
	ds_read_b128 v[60:63], v205 offset:192
	s_waitcnt lgkmcnt(2)
	v_mfma_f32_32x32x16_bf16 v[18:33], v[68:71], v[114:117], v[18:33]
	v_fma_f32 v68, -v76, v77, 1.0
	v_fmac_f32_e32 v77, v68, v77
	ds_read_b128 v[68:71], v205 offset:224
	v_mul_f32_e32 v85, v78, v77
	s_waitcnt lgkmcnt(2)
	v_mfma_f32_32x32x16_bf16 v[18:33], v[86:89], v[118:121], v[18:33]
	v_fma_f32 v86, -v76, v85, v78
	v_fmac_f32_e32 v85, v86, v77
	v_mfma_f32_32x32x16_bf16 v[2:17], v[64:67], v[106:109], v[2:17]
	s_waitcnt lgkmcnt(1)
	v_mfma_f32_32x32x16_bf16 v[18:33], v[60:63], v[122:125], v[18:33]
	v_fma_f32 v60, -v76, v85, v78
	v_div_fmas_f32 v60, v60, v77, v85
	v_div_fixup_f32 v60, v60, v59, 1.0
	v_cmp_lt_f32_e32 vcc, 0, v59
	v_lshlrev_b32_e32 v59, 9, v147
	s_nop 0
	v_cndmask_b32_e32 v158, 0, v60, vcc
	v_mfma_f32_32x32x16_bf16 v[2:17], v[72:75], v[110:113], v[2:17]
	v_cmp_neq_f32_e32 vcc, s25, v155
	s_nop 1
	v_cndmask_b32_e32 v155, 0, v155, vcc
	s_waitcnt lgkmcnt(0)
	v_mfma_f32_32x32x16_bf16 v[18:33], v[68:71], v[126:129], v[18:33]
	ds_read_b128 v[60:63], v205 offset:8832
	ds_read_b128 v[68:71], v205 offset:8864
	s_waitcnt lgkmcnt(1)
	v_mfma_f32_32x32x16_bf16 v[2:17], v[60:63], v[114:117], v[2:17]
	s_nop 7
	v_sub_f32_e32 v18, v18, v84
	v_sub_f32_e32 v19, v19, v81
	v_sub_f32_e32 v20, v20, v82
	v_sub_f32_e32 v21, v21, v83
	v_cndmask_b32_e64 v18, v18, v230, s[88:89]
	v_cndmask_b32_e64 v19, v19, v230, s[94:95]
	v_cndmask_b32_e64 v20, v20, v230, s[4:5]
	s_waitcnt lgkmcnt(0)
	v_mfma_f32_32x32x16_bf16 v[2:17], v[68:71], v[118:121], v[2:17]
	v_cndmask_b32_e64 v21, v21, v230, s[10:11]
	ds_read_b128 v[62:65], v205 offset:8896
	ds_read_b128 v[72:75], v205 offset:8928
	v_sub_f32_e32 v18, v18, v155
	v_sub_f32_e32 v19, v19, v155
	v_sub_f32_e32 v20, v20, v155
	v_sub_f32_e32 v21, v21, v155
	v_exp_f32_e32 v18, v18
	v_exp_f32_e32 v19, v19
	v_exp_f32_e32 v20, v20
	v_exp_f32_e32 v21, v21
	s_waitcnt lgkmcnt(1)
	v_mfma_f32_32x32x16_bf16 v[2:17], v[62:65], v[122:125], v[2:17]
	v_mul_f32_e64 v18, v158, v18
	v_mul_f32_e64 v19, v158, v19
	v_add_f32_e32 v66, v18, v19
	v_mul_f32_e64 v20, v158, v20
	v_mul_f32_e64 v21, v158, v21
	v_add_f32_e32 v61, v20, v21
	v_add_f32_e32 v66, v66, v61
	s_nop 1
	v_mov_b32_dpp v67, v66 quad_perm:[1,0,3,2] row_mask:0xf bank_mask:0xf
	s_nop 1
	v_mov_b32_dpp v68, v21 quad_perm:[1,0,3,2] row_mask:0xf bank_mask:0xf
	s_waitcnt lgkmcnt(0)
	v_mfma_f32_32x32x16_bf16 v[2:17], v[72:75], v[126:129], v[2:17]
	v_readlane_b32 s4, v254, 24
	v_add_u32_e32 v60, s19, v59
	s_waitcnt lgkmcnt(0)
	v_add_f32_e32 v64, v66, v67
	s_waitcnt lgkmcnt(0)
	v_add_f32_e32 v66, v21, v68
	s_nop 1
	v_mov_b32_dpp v65, v64 quad_perm:[2,3,0,1] row_mask:0xf bank_mask:0xf
	s_nop 1
	v_mov_b32_dpp v67, v66 quad_perm:[2,3,0,1] row_mask:0xf bank_mask:0xf
	v_add_u32_e32 v59, s4, v59
	s_and_b32 s4, s0, 0x70
	v_or_b32_e32 v61, s4, v201
	v_lshlrev_b32_e32 v63, 2, v61
	v_add_u32_e32 v62, v59, v63
	v_add_u32_e32 v63, v60, v63
	s_and_saveexec_b64 s[4:5], s[46:47]
	s_cbranch_execz .LBB0_627
	s_waitcnt lgkmcnt(0)
	v_add_f32_e32 v64, v64, v65
	s_waitcnt lgkmcnt(0)
	v_add_f32_e32 v65, v66, v67
	ds_write_b32 v63, v64
	ds_write_b32 v62, v65 offset:4
.LBB0_627:
	s_or_b64 exec, exec, s[4:5]
	v_sub_f32_e32 v22, v22, v79
	v_sub_f32_e32 v23, v23, v80
	v_sub_f32_e32 v24, v24, v57
	v_sub_f32_e32 v25, v25, v58
	v_cndmask_b32_e64 v22, v22, v230, s[80:81]
	v_cndmask_b32_e64 v23, v23, v230, s[82:83]
	v_cndmask_b32_e64 v24, v24, v230, s[86:87]
	v_cndmask_b32_e64 v25, v25, v230, s[92:93]
	v_sub_f32_e32 v22, v22, v155
	v_sub_f32_e32 v23, v23, v155
	v_sub_f32_e32 v24, v24, v155
	v_sub_f32_e32 v25, v25, v155
	v_exp_f32_e32 v22, v22
	v_exp_f32_e32 v23, v23
	v_exp_f32_e32 v24, v24
	v_exp_f32_e32 v25, v25
	v_mov_b32_e32 v159, v158
	v_pk_mul_f32 v[22:23], v[158:159], v[22:23]
	v_pk_mul_f32 v[24:25], v[158:159], v[24:25]
	s_nop 0
	v_add_f32_e32 v57, v24, v25
	v_add_f32_e32 v58, v22, v23
	v_add_f32_e32 v57, v58, v57
	s_nop 1
	v_mov_b32_dpp v58, v57 quad_perm:[1,0,3,2] row_mask:0xf bank_mask:0xf
	s_nop 1
	v_mov_b32_dpp v64, v25 quad_perm:[1,0,3,2] row_mask:0xf bank_mask:0xf
	s_waitcnt lgkmcnt(0)
	v_add_f32_e32 v57, v57, v58
	s_waitcnt lgkmcnt(0)
	v_add_f32_e32 v64, v25, v64
	s_nop 1
	v_mov_b32_dpp v58, v57 quad_perm:[2,3,0,1] row_mask:0xf bank_mask:0xf
	s_nop 1
	v_mov_b32_dpp v65, v64 quad_perm:[2,3,0,1] row_mask:0xf bank_mask:0xf
	s_and_saveexec_b64 s[4:5], s[46:47]
	v_readlane_b32 s80, v254, 38
	v_readlane_b32 s86, v254, 41
	v_readlane_b32 s88, v254, 43
	v_readlane_b32 s92, v254, 45
	v_readlane_b32 s94, v254, 47
	v_readlane_b32 s81, v254, 39
	v_readlane_b32 s82, v254, 40
	v_readlane_b32 s87, v254, 42
	v_readlane_b32 s89, v254, 44
	v_readlane_b32 s93, v254, 46
	v_readlane_b32 s95, v254, 48
	v_readlane_b32 s28, v254, 49
	v_readlane_b32 s29, v254, 50
	s_movk_i32 s39, 0x200
	s_cbranch_execz .LBB0_629
	s_waitcnt lgkmcnt(0)
	v_add_f32_e32 v57, v57, v58
	s_waitcnt lgkmcnt(0)
	v_add_f32_e32 v58, v64, v65
	ds_write_b32 v63, v57 offset:8
	ds_write_b32 v62, v58 offset:12
; #define LAS __attribute__((address_space(3)))
; DI float shx(float v, int m, int lane) { return __builtin_bit_cast(float, __builtin_amdgcn_ds_bpermute((lane ^ m) << 2, __builtin_bit_cast(int, v))); }
; DI float fexp2(float x) { return __builtin_amdgcn_exp2f(x); }
; template <int MODE> DI void attn_h2(AttnCtx& c, f32x16 (&o)[4], f32x16& s0, f32x16& s1, ldsp lds, int vbuf, int tj, int lane) {
;     ...
;                 for (int e = 0; e < 16; ++e) { s0[e] = fexp2(s0[e] - c.m) * c.l; s1[e] = fexp2(s1[e] - c.m) * c.l; }
;                 LAS float* impg = (LAS float*)(lds + A_IMPG) + c.qi * 128; LAS float* imp3 = (LAS float*)(lds + A_IMP3) + c.qi * 128;
; #pragma unroll
;                 for (int kb = 0; kb < 2; ++kb)
; #pragma unroll
;                     for (int g4 = 0; g4 < 4; ++g4) {
;                         float G, p3;
;                         if (kb == 0) { G = (s0[4 * g4] + s0[4 * g4 + 1]) + (s0[4 * g4 + 2] + s0[4 * g4 + 3]); p3 = s0[4 * g4 + 3]; }
;                         else { G = (s1[4 * g4] + s1[4 * g4 + 1]) + (s1[4 * g4 + 2] + s1[4 * g4 + 3]); p3 = s1[4 * g4 + 3]; }
;                         G += shx(G, 1, lane); G += shx(G, 2, lane); p3 += shx(p3, 1, lane); p3 += shx(p3, 2, lane);
;                         const int n4 = tj * 16 + kb * 8 + 2 * g4 + h;
;                         if ((lane & 3) == 0) { impg[n4] = G; if (n4 + 1 < 128) imp3[n4 + 1] = p3; }
;                     }
.LBB0_629:
	s_or_b64 exec, exec, s[4:5]
	v_sub_f32_e32 v26, v26, v53
	v_sub_f32_e32 v27, v27, v54
	v_sub_f32_e32 v28, v28, v55
	v_sub_f32_e32 v29, v29, v56
	v_cndmask_b32_e64 v26, v26, v230, s[84:85]
	v_cndmask_b32_e64 v27, v27, v230, s[90:91]
	v_cndmask_b32_e64 v28, v28, v230, s[2:3]
	v_cndmask_b32_e64 v29, v29, v230, s[8:9]
	v_sub_f32_e32 v26, v26, v155
	v_sub_f32_e32 v27, v27, v155
	v_sub_f32_e32 v28, v28, v155
	v_sub_f32_e32 v29, v29, v155
	v_exp_f32_e32 v26, v26
	v_exp_f32_e32 v27, v27
	v_exp_f32_e32 v28, v28
	v_exp_f32_e32 v29, v29
	v_pk_mul_f32 v[70:71], v[158:159], v[26:27]
	s_nop 0
	v_add_f32_e32 v27, v70, v71
	v_pk_mul_f32 v[72:73], v[158:159], v[28:29]
	s_nop 1
	v_mov_b32_dpp v28, v73 quad_perm:[1,0,3,2] row_mask:0xf bank_mask:0xf
	v_add_f32_e32 v26, v72, v73
	v_add_f32_e32 v26, v27, v26
	s_nop 1
	v_mov_b32_dpp v27, v26 quad_perm:[1,0,3,2] row_mask:0xf bank_mask:0xf
	s_waitcnt lgkmcnt(0)
	v_add_f32_e32 v28, v73, v28
	s_nop 1
	v_mov_b32_dpp v29, v28 quad_perm:[2,3,0,1] row_mask:0xf bank_mask:0xf
	s_waitcnt lgkmcnt(0)
	v_add_f32_e32 v26, v26, v27
	s_nop 1
	v_mov_b32_dpp v27, v26 quad_perm:[2,3,0,1] row_mask:0xf bank_mask:0xf
	s_and_saveexec_b64 s[2:3], s[46:47]
	s_cbranch_execz .LBB0_631
	s_waitcnt lgkmcnt(0)
	v_add_f32_e32 v26, v26, v27
	v_add_f32_e32 v27, v28, v29
	ds_write_b32 v63, v26 offset:16
	ds_write_b32 v62, v27 offset:20
.LBB0_631:
	s_or_b64 exec, exec, s[2:3]
	v_sub_f32_e32 v26, v30, v49
	s_waitcnt lgkmcnt(0)
	v_sub_f32_e32 v27, v31, v50
	v_sub_f32_e32 v28, v32, v51
	v_sub_f32_e32 v29, v33, v52
	v_cndmask_b32_e64 v26, v26, v230, s[96:97]
	v_cndmask_b32_e64 v27, v27, v230, s[6:7]
	v_cndmask_b32_e64 v28, v28, v230, s[12:13]
	v_cndmask_b32_e64 v29, v29, v230, s[14:15]
	v_sub_f32_e32 v26, v26, v155
	v_sub_f32_e32 v27, v27, v155
	v_sub_f32_e32 v28, v28, v155
	v_sub_f32_e32 v29, v29, v155
	v_exp_f32_e32 v26, v26
	v_exp_f32_e32 v27, v27
	v_exp_f32_e32 v28, v28
	v_exp_f32_e32 v29, v29
	v_pk_mul_f32 v[82:83], v[158:159], v[26:27]
	s_nop 0
	v_add_f32_e32 v27, v82, v83
	v_pk_mul_f32 v[84:85], v[158:159], v[28:29]
	s_nop 1
	v_mov_b32_dpp v28, v85 quad_perm:[1,0,3,2] row_mask:0xf bank_mask:0xf
	v_add_f32_e32 v26, v84, v85
	v_add_f32_e32 v26, v27, v26
	s_nop 1
	v_mov_b32_dpp v27, v26 quad_perm:[1,0,3,2] row_mask:0xf bank_mask:0xf
	s_waitcnt lgkmcnt(0)
	v_add_f32_e32 v28, v85, v28
	s_nop 1
	v_mov_b32_dpp v29, v28 quad_perm:[2,3,0,1] row_mask:0xf bank_mask:0xf
	s_waitcnt lgkmcnt(0)
	v_add_f32_e32 v26, v26, v27
	s_nop 1
	v_mov_b32_dpp v27, v26 quad_perm:[2,3,0,1] row_mask:0xf bank_mask:0xf
	s_and_saveexec_b64 s[2:3], s[46:47]
	s_cbranch_execz .LBB0_633
	s_waitcnt lgkmcnt(0)
	v_add_f32_e32 v26, v26, v27
	v_add_f32_e32 v27, v28, v29
	ds_write_b32 v63, v26 offset:24
	ds_write_b32 v62, v27 offset:28
.LBB0_633:
	s_or_b64 exec, exec, s[2:3]
	v_sub_f32_e32 v2, v2, v45
	v_sub_f32_e32 v3, v3, v46
	v_sub_f32_e32 v4, v4, v47
	v_sub_f32_e32 v5, v5, v48
	v_cndmask_b32_e64 v2, v2, v230, s[48:49]
	v_cndmask_b32_e64 v3, v3, v230, s[50:51]
	v_cndmask_b32_e64 v4, v4, v230, s[54:55]
	v_cndmask_b32_e64 v5, v5, v230, s[58:59]
	v_sub_f32_e32 v2, v2, v155
	v_sub_f32_e32 v3, v3, v155
	v_sub_f32_e32 v4, v4, v155
	v_sub_f32_e32 v5, v5, v155
	v_exp_f32_e32 v2, v2
	v_exp_f32_e32 v3, v3
	v_exp_f32_e32 v4, v4
	v_exp_f32_e32 v5, v5
	v_pk_mul_f32 v[66:67], v[158:159], v[2:3]
	s_nop 0
	v_add_f32_e32 v3, v66, v67
	v_pk_mul_f32 v[68:69], v[158:159], v[4:5]
	s_nop 1
	v_mov_b32_dpp v4, v69 quad_perm:[1,0,3,2] row_mask:0xf bank_mask:0xf
	v_add_f32_e32 v2, v68, v69
	v_add_f32_e32 v2, v3, v2
	s_nop 1
	v_mov_b32_dpp v3, v2 quad_perm:[1,0,3,2] row_mask:0xf bank_mask:0xf
	s_waitcnt lgkmcnt(0)
	v_add_f32_e32 v4, v69, v4
	s_nop 1
	v_mov_b32_dpp v5, v4 quad_perm:[2,3,0,1] row_mask:0xf bank_mask:0xf
	s_waitcnt lgkmcnt(0)
	v_add_f32_e32 v2, v2, v3
	s_nop 1
	v_mov_b32_dpp v3, v2 quad_perm:[2,3,0,1] row_mask:0xf bank_mask:0xf
	s_and_saveexec_b64 s[2:3], s[46:47]
	s_cbranch_execz .LBB0_635
	s_waitcnt lgkmcnt(0)
	v_add_f32_e32 v2, v2, v3
	v_add_f32_e32 v3, v4, v5
	ds_write_b32 v63, v2 offset:32
	ds_write_b32 v62, v3 offset:36
; #define LAS __attribute__((address_space(3)))
; DI float shx(float v, int m, int lane) { return __builtin_bit_cast(float, __builtin_amdgcn_ds_bpermute((lane ^ m) << 2, __builtin_bit_cast(int, v))); }
; DI float fexp2(float x) { return __builtin_amdgcn_exp2f(x); }
; template <int MODE> DI void attn_h2(AttnCtx& c, f32x16 (&o)[4], f32x16& s0, f32x16& s1, ldsp lds, int vbuf, int tj, int lane) {
;     ...
;                 for (int e = 0; e < 16; ++e) { s0[e] = fexp2(s0[e] - c.m) * c.l; s1[e] = fexp2(s1[e] - c.m) * c.l; }
;                 LAS float* impg = (LAS float*)(lds + A_IMPG) + c.qi * 128; LAS float* imp3 = (LAS float*)(lds + A_IMP3) + c.qi * 128;
; #pragma unroll
;                 for (int kb = 0; kb < 2; ++kb)
; #pragma unroll
;                     for (int g4 = 0; g4 < 4; ++g4) {
;                         float G, p3;
;                         if (kb == 0) { G = (s0[4 * g4] + s0[4 * g4 + 1]) + (s0[4 * g4 + 2] + s0[4 * g4 + 3]); p3 = s0[4 * g4 + 3]; }
;                         else { G = (s1[4 * g4] + s1[4 * g4 + 1]) + (s1[4 * g4 + 2] + s1[4 * g4 + 3]); p3 = s1[4 * g4 + 3]; }
;                         G += shx(G, 1, lane); G += shx(G, 2, lane); p3 += shx(p3, 1, lane); p3 += shx(p3, 2, lane);
;                         const int n4 = tj * 16 + kb * 8 + 2 * g4 + h;
;                         if ((lane & 3) == 0) { impg[n4] = G; if (n4 + 1 < 128) imp3[n4 + 1] = p3; }
;                     }
.LBB0_635:
	s_or_b64 exec, exec, s[2:3]
	v_sub_f32_e32 v2, v6, v41
	s_waitcnt lgkmcnt(0)
	v_sub_f32_e32 v3, v7, v42
	v_sub_f32_e32 v4, v8, v43
	v_sub_f32_e32 v5, v9, v44
	v_cndmask_b32_e64 v2, v2, v230, s[52:53]
	v_cndmask_b32_e64 v3, v3, v230, s[56:57]
	v_cndmask_b32_e64 v4, v4, v230, s[62:63]
	v_cndmask_b32_e64 v5, v5, v230, s[66:67]
	v_sub_f32_e32 v2, v2, v155
	v_sub_f32_e32 v3, v3, v155
	v_sub_f32_e32 v4, v4, v155
	v_sub_f32_e32 v5, v5, v155
	v_exp_f32_e32 v2, v2
	v_exp_f32_e32 v3, v3
	v_exp_f32_e32 v4, v4
	v_exp_f32_e32 v5, v5
	v_pk_mul_f32 v[78:79], v[158:159], v[2:3]
	s_nop 0
	v_add_f32_e32 v3, v78, v79
	v_pk_mul_f32 v[80:81], v[158:159], v[4:5]
	s_nop 1
	v_mov_b32_dpp v4, v81 quad_perm:[1,0,3,2] row_mask:0xf bank_mask:0xf
	v_add_f32_e32 v2, v80, v81
	v_add_f32_e32 v2, v3, v2
	s_nop 1
	v_mov_b32_dpp v3, v2 quad_perm:[1,0,3,2] row_mask:0xf bank_mask:0xf
	s_waitcnt lgkmcnt(0)
	v_add_f32_e32 v4, v81, v4
	s_nop 1
	v_mov_b32_dpp v5, v4 quad_perm:[2,3,0,1] row_mask:0xf bank_mask:0xf
	s_waitcnt lgkmcnt(0)
	v_add_f32_e32 v2, v2, v3
	s_nop 1
	v_mov_b32_dpp v3, v2 quad_perm:[2,3,0,1] row_mask:0xf bank_mask:0xf
	s_and_saveexec_b64 s[2:3], s[46:47]
	s_cbranch_execz .LBB0_637
	s_waitcnt lgkmcnt(0)
	v_add_f32_e32 v2, v2, v3
	v_add_f32_e32 v3, v4, v5
	ds_write_b32 v63, v2 offset:40
	ds_write_b32 v62, v3 offset:44
.LBB0_637:
	s_or_b64 exec, exec, s[2:3]
	v_sub_f32_e32 v2, v10, v37
	s_waitcnt lgkmcnt(0)
	v_sub_f32_e32 v3, v11, v38
	v_sub_f32_e32 v4, v12, v39
	v_sub_f32_e32 v5, v13, v40
	v_cndmask_b32_e64 v2, v2, v230, s[60:61]
	v_cndmask_b32_e64 v3, v3, v230, s[64:65]
	v_cndmask_b32_e64 v4, v4, v230, s[70:71]
	v_cndmask_b32_e64 v5, v5, v230, s[74:75]
	v_sub_f32_e32 v2, v2, v155
	v_sub_f32_e32 v3, v3, v155
	v_sub_f32_e32 v4, v4, v155
	v_sub_f32_e32 v5, v5, v155
	v_exp_f32_e32 v2, v2
	v_exp_f32_e32 v3, v3
	v_exp_f32_e32 v4, v4
	v_exp_f32_e32 v5, v5
	v_pk_mul_f32 v[74:75], v[158:159], v[2:3]
	s_nop 0
	v_add_f32_e32 v3, v74, v75
	v_pk_mul_f32 v[76:77], v[158:159], v[4:5]
	s_nop 1
	v_mov_b32_dpp v4, v77 quad_perm:[1,0,3,2] row_mask:0xf bank_mask:0xf
	v_add_f32_e32 v2, v76, v77
	v_add_f32_e32 v2, v3, v2
	s_nop 1
	v_mov_b32_dpp v3, v2 quad_perm:[1,0,3,2] row_mask:0xf bank_mask:0xf
	s_waitcnt lgkmcnt(0)
	v_add_f32_e32 v4, v77, v4
	s_nop 1
	v_mov_b32_dpp v5, v4 quad_perm:[2,3,0,1] row_mask:0xf bank_mask:0xf
	s_waitcnt lgkmcnt(0)
	v_add_f32_e32 v2, v2, v3
	s_nop 1
	v_mov_b32_dpp v3, v2 quad_perm:[2,3,0,1] row_mask:0xf bank_mask:0xf
	s_and_saveexec_b64 s[2:3], s[46:47]
	s_cbranch_execz .LBB0_639
	s_waitcnt lgkmcnt(0)
	v_add_f32_e32 v2, v2, v3
	v_add_f32_e32 v3, v4, v5
	ds_write_b32 v63, v2 offset:48
	ds_write_b32 v62, v3 offset:52
.LBB0_639:
	s_or_b64 exec, exec, s[2:3]
	v_sub_f32_e32 v0, v14, v0
	v_sub_f32_e32 v2, v15, v34
	v_cndmask_b32_e64 v0, v0, v230, s[68:69]
	s_waitcnt lgkmcnt(0)
	v_cndmask_b32_e64 v3, v2, v230, s[72:73]
	v_sub_f32_e32 v2, v16, v35
	v_cndmask_b32_e64 v4, v2, v230, s[76:77]
	v_sub_f32_e32 v2, v17, v36
	v_sub_f32_e32 v0, v0, v155
	v_cndmask_b32_e64 v5, v2, v230, s[78:79]
	v_exp_f32_e32 v2, v0
	v_sub_f32_e32 v0, v3, v155
	v_exp_f32_e32 v3, v0
	v_sub_f32_e32 v0, v4, v155
	v_exp_f32_e32 v4, v0
	v_sub_f32_e32 v0, v5, v155
	v_exp_f32_e32 v5, v0
	v_pk_mul_f32 v[86:87], v[158:159], v[2:3]
	v_pk_mul_f32 v[88:89], v[158:159], v[4:5]
	s_nop 0
	v_add_f32_e32 v0, v88, v89
	v_add_f32_e32 v2, v86, v87
	v_add_f32_e32 v0, v2, v0
	s_nop 1
	v_mov_b32_dpp v2, v0 quad_perm:[1,0,3,2] row_mask:0xf bank_mask:0xf
	s_nop 1
	v_mov_b32_dpp v5, v89 quad_perm:[1,0,3,2] row_mask:0xf bank_mask:0xf
	s_waitcnt lgkmcnt(0)
	v_add_f32_e32 v3, v0, v2
	s_waitcnt lgkmcnt(0)
	v_add_f32_e32 v0, v89, v5
	s_nop 1
	v_mov_b32_dpp v4, v3 quad_perm:[2,3,0,1] row_mask:0xf bank_mask:0xf
	s_nop 1
	v_mov_b32_dpp v2, v0 quad_perm:[2,3,0,1] row_mask:0xf bank_mask:0xf
	s_and_saveexec_b64 s[2:3], s[46:47]
	s_cbranch_execz .LBB0_642
	s_movk_i32 s4, 0x71
	s_waitcnt lgkmcnt(0)
	v_add_f32_e32 v3, v3, v4
	v_lshl_add_u32 v4, v61, 2, v60
	v_cmp_ne_u32_e32 vcc, s4, v61
	ds_write_b32 v4, v3 offset:56
	s_and_b64 exec, exec, vcc
	s_cbranch_execz .LBB0_642
	s_waitcnt lgkmcnt(0)
	v_add_f32_e32 v0, v0, v2
	v_lshl_add_u32 v2, v61, 2, v59
	ds_write_b32 v2, v0 offset:60

; #define LAS __attribute__((address_space(3)))
; template <int MODE> DI void attn_h1(AttnCtx& c, const bf16x8 (&q)[8], f32x16 (&o)[4], f32x16& s0, f32x16& s1, ldsp lds, int kbuf, int bbuf, int tj, int lane) {
;     ...
;             ldsp kl = lds + kbuf + r32 * KPITCH + h * 16;
; #pragma unroll
;             for (int e = 0; e < 16; ++e) { s0[e] = 0.f; s1[e] = 0.f; }
; #pragma unroll
;             for (int s = 0; s < 8; ++s) {
;                 const bf16x8 ka = *(const LAS bf16x8*)(kl + s * 32), kb = *(const LAS bf16x8*)(kl + 32 * KPITCH + s * 32);
;                 s0 = MFMA32(ka, q[s], s0); s1 = MFMA32(kb, q[s], s1);
;     ...
;                     for (int e = 0; e < 16; ++e) {
;                         const float d0 = dbase - (float)(PS * (8 * (e >> 2) + (e & 3))), d1 = d0 - (float)(PS * 32);
;                         bool v0 = d0 >= 0.f, v1 = d1 >= 0.f;
;                         if (MODE == MD_WIN) { v0 = v0 && d0 < 512.f; v1 = v1 && d1 < 512.f; }
;                         if (MODE == MD_SEL) { v0 = v0 && selbit; v1 = v1 && selbit; }
;                         s0[e] = v0 ? s0[e] - c.slope2 * d0 : NINF;
;                         s1[e] = v1 ? s1[e] - c.slope2 * d1 : NINF;
;                     }
; template <int MODE> DI void attn_h2(AttnCtx& c, f32x16 (&o)[4], f32x16& s0, f32x16& s1, ldsp lds, int vbuf, int tj, int lane) {
;     ...
;             if (MODE == MD_CMP2) {
; #pragma unroll
;                 for (int e = 0; e < 16; ++e) { s0[e] = fexp2(s0[e] - c.m) * c.l; s1[e] = fexp2(s1[e] - c.m) * c.l; }
;                 LAS float* impg = (LAS float*)(lds + A_IMPG) + c.qi * 128; LAS float* imp3 = (LAS float*)(lds + A_IMP3) + c.qi * 128;
; #pragma unroll
;                 for (int kb = 0; kb < 2; ++kb)
; #pragma unroll
;                     for (int g4 = 0; g4 < 4; ++g4) {
;                         float G, p3;
;                         if (kb == 0) { G = (s0[4 * g4] + s0[4 * g4 + 1]) + (s0[4 * g4 + 2] + s0[4 * g4 + 3]); p3 = s0[4 * g4 + 3]; }
;                         else { G = (s1[4 * g4] + s1[4 * g4 + 1]) + (s1[4 * g4 + 2] + s1[4 * g4 + 3]); p3 = s1[4 * g4 + 3]; }
;                         G += shx(G, 1, lane); G += shx(G, 2, lane); p3 += shx(p3, 1, lane); p3 += shx(p3, 2, lane);
;                         const int n4 = tj * 16 + kb * 8 + 2 * g4 + h;
;                         if ((lane & 3) == 0) { impg[n4] = G; if (n4 + 1 < 128) imp3[n4 + 1] = p3; }
;                     }
.LBB0_661:
	s_mul_i32 s8, s15, 0x4400
	v_add_u32_e32 v186, s8, v205
	ds_read_b128 v[66:69], v186 offset:8704
	ds_read_b128 v[70:73], v186
	ds_read_b128 v[178:181], v186 offset:32
	ds_read_b128 v[182:185], v186 offset:8736
	s_waitcnt lgkmcnt(2)
	v_mfma_f32_32x32x16_bf16 v[82:97], v[70:73], v[98:101], 0
	v_mfma_f32_32x32x16_bf16 v[66:81], v[66:69], v[98:101], 0
	s_waitcnt lgkmcnt(1)
	v_mfma_f32_32x32x16_bf16 v[82:97], v[178:181], v[102:105], v[82:97]
	s_waitcnt lgkmcnt(0)
	v_mfma_f32_32x32x16_bf16 v[66:81], v[182:185], v[102:105], v[66:81]
	ds_read_b128 v[178:181], v186 offset:8768
	ds_read_b128 v[182:185], v186 offset:64
	s_waitcnt lgkmcnt(0)
	v_mfma_f32_32x32x16_bf16 v[82:97], v[182:185], v[106:109], v[82:97]
	v_mfma_f32_32x32x16_bf16 v[66:81], v[178:181], v[106:109], v[66:81]
	ds_read_b128 v[178:181], v186 offset:8800
	ds_read_b128 v[182:185], v186 offset:96
	s_waitcnt lgkmcnt(0)
	v_mfma_f32_32x32x16_bf16 v[82:97], v[182:185], v[110:113], v[82:97]
	v_mfma_f32_32x32x16_bf16 v[66:81], v[178:181], v[110:113], v[66:81]
	ds_read_b128 v[178:181], v186 offset:8832
	ds_read_b128 v[182:185], v186 offset:128
	ds_read_b128 v[210:213], v186 offset:160
	s_waitcnt lgkmcnt(1)
	v_mfma_f32_32x32x16_bf16 v[82:97], v[182:185], v[114:117], v[82:97]
	v_mfma_f32_32x32x16_bf16 v[66:81], v[178:181], v[114:117], v[66:81]
	ds_read_b128 v[178:181], v186 offset:8864
	s_waitcnt lgkmcnt(1)
	v_mfma_f32_32x32x16_bf16 v[82:97], v[210:213], v[118:121], v[82:97]
	s_waitcnt lgkmcnt(0)
	v_mfma_f32_32x32x16_bf16 v[66:81], v[178:181], v[118:121], v[66:81]
	ds_read_b128 v[178:181], v186 offset:8896
	ds_read_b128 v[182:185], v186 offset:192
	s_waitcnt lgkmcnt(0)
	v_mfma_f32_32x32x16_bf16 v[82:97], v[182:185], v[122:125], v[82:97]
	v_mfma_f32_32x32x16_bf16 v[66:81], v[178:181], v[122:125], v[66:81]
	ds_read_b128 v[178:181], v186 offset:8928
	ds_read_b128 v[182:185], v186 offset:224
	s_waitcnt lgkmcnt(0)
	v_mfma_f32_32x32x16_bf16 v[82:97], v[182:185], v[126:129], v[82:97]
	v_mfma_f32_32x32x16_bf16 v[66:81], v[178:181], v[126:129], v[66:81]
	v_add3_u32 v178, v172, v175, -16
	v_cvt_f32_i32_e32 v179, v178
	v_cmp_lt_i32_e32 vcc, -1, v178
	s_nop 7
	v_fma_f32 v82, -v146, v179, v82
	v_add_f32_e32 v180, 0xc1800000, v179
	v_cndmask_b32_e32 v82, v230, v82, vcc
	v_fma_f32 v83, -v146, v180, v83
	v_cmp_le_f32_e32 vcc, 0, v180
	v_add_f32_e32 v181, 0xc2000000, v179
	v_fma_f32 v84, -v146, v181, v84
	v_cndmask_b32_e32 v83, v230, v83, vcc
	v_cmp_le_f32_e32 vcc, 0, v181
	v_add_f32_e32 v182, 0xc2400000, v179
	v_fma_f32 v85, -v146, v182, v85
	v_cndmask_b32_e32 v84, v230, v84, vcc
	v_cmp_le_f32_e32 vcc, 0, v182
	v_sub_f32_e32 v82, v82, v155
	v_sub_f32_e32 v83, v83, v155
	v_cndmask_b32_e32 v85, v230, v85, vcc
	v_sub_f32_e32 v84, v84, v155
	v_sub_f32_e32 v85, v85, v155
	v_exp_f32_e32 v82, v82
	v_exp_f32_e32 v83, v83
	v_exp_f32_e32 v84, v84
	v_exp_f32_e32 v85, v85
	v_pk_mul_f32 v[82:83], v[158:159], v[82:83]
	s_nop 0
	v_add_f32_e32 v183, v82, v83
	v_pk_mul_f32 v[84:85], v[158:159], v[84:85]
	s_nop 0
	v_add_f32_e32 v178, v84, v85
	v_add_f32_e32 v178, v183, v178
	s_nop 1
	v_mov_b32_dpp v183, v178 quad_perm:[1,0,3,2] row_mask:0xf bank_mask:0xf
	s_waitcnt lgkmcnt(0)
	v_add_f32_e32 v183, v178, v183
	s_nop 1
	v_mov_b32_dpp v178, v85 quad_perm:[1,0,3,2] row_mask:0xf bank_mask:0xf
	s_nop 1
	v_mov_b32_dpp v184, v183 quad_perm:[2,3,0,1] row_mask:0xf bank_mask:0xf
	s_waitcnt lgkmcnt(0)
	v_add_f32_e32 v185, v85, v178
	s_nop 1
	v_mov_b32_dpp v186, v185 quad_perm:[2,3,0,1] row_mask:0xf bank_mask:0xf
	v_add_u32_e32 v178, s11, v176
	s_and_saveexec_b64 s[8:9], s[46:47]
	s_cbranch_execz .LBB0_663
	v_add_u32_e32 v190, 0x119c0, v178
	s_waitcnt lgkmcnt(0)
	v_add_f32_e32 v183, v183, v184
	v_add_u32_e32 v187, 0x199c4, v178
	s_waitcnt lgkmcnt(0)
	v_add_f32_e32 v184, v185, v186
	ds_write_b32 v190, v183
	ds_write_b32 v187, v184
.LBB0_663:
	s_or_b64 exec, exec, s[8:9]
	v_add_f32_e32 v183, 0xc3000000, v179
	v_fma_f32 v86, -v146, v183, v86
	v_cmp_le_f32_e32 vcc, 0, v183
	s_waitcnt lgkmcnt(0)
	v_add_f32_e32 v184, 0xc3100000, v179
	v_fma_f32 v87, -v146, v184, v87
	v_cndmask_b32_e32 v86, v230, v86, vcc
	v_cmp_le_f32_e32 vcc, 0, v184
	v_add_f32_e32 v185, 0xc3200000, v179
	v_fma_f32 v88, -v146, v185, v88
	v_cndmask_b32_e32 v87, v230, v87, vcc
	v_cmp_le_f32_e32 vcc, 0, v185
	s_waitcnt lgkmcnt(0)
	v_add_f32_e32 v186, 0xc3300000, v179
	v_fma_f32 v89, -v146, v186, v89
	v_cndmask_b32_e32 v88, v230, v88, vcc
	v_cmp_le_f32_e32 vcc, 0, v186
	v_sub_f32_e32 v86, v86, v155
	v_sub_f32_e32 v87, v87, v155
	v_cndmask_b32_e32 v89, v230, v89, vcc
	v_sub_f32_e32 v88, v88, v155
	v_sub_f32_e32 v89, v89, v155
	v_exp_f32_e32 v86, v86
	v_exp_f32_e32 v87, v87
	v_exp_f32_e32 v88, v88
	v_exp_f32_e32 v89, v89
	v_pk_mul_f32 v[86:87], v[158:159], v[86:87]
	s_nop 0
	v_add_f32_e32 v190, v86, v87
	v_pk_mul_f32 v[88:89], v[158:159], v[88:89]
	s_nop 1
	v_mov_b32_dpp v209, v89 quad_perm:[1,0,3,2] row_mask:0xf bank_mask:0xf
	v_add_f32_e32 v187, v88, v89
	v_add_f32_e32 v187, v190, v187
	s_nop 1
	v_mov_b32_dpp v190, v187 quad_perm:[1,0,3,2] row_mask:0xf bank_mask:0xf
	s_waitcnt lgkmcnt(0)
	v_add_f32_e32 v209, v89, v209
	s_nop 1
	v_mov_b32_dpp v210, v209 quad_perm:[2,3,0,1] row_mask:0xf bank_mask:0xf
	s_waitcnt lgkmcnt(0)
	v_add_f32_e32 v187, v187, v190
	s_nop 1
	v_mov_b32_dpp v190, v187 quad_perm:[2,3,0,1] row_mask:0xf bank_mask:0xf
	s_and_saveexec_b64 s[8:9], s[46:47]
	s_cbranch_execz .LBB0_665
	v_add_u32_e32 v212, 0x119c8, v178
	s_waitcnt lgkmcnt(0)
	v_add_f32_e32 v187, v187, v190
	v_add_u32_e32 v211, 0x199cc, v178
	v_add_f32_e32 v190, v209, v210
	ds_write_b32 v212, v187
	ds_write_b32 v211, v190
; #define LAS __attribute__((address_space(3)))
; DI float shx(float v, int m, int lane) { return __builtin_bit_cast(float, __builtin_amdgcn_ds_bpermute((lane ^ m) << 2, __builtin_bit_cast(int, v))); }
; DI float fexp2(float x) { return __builtin_amdgcn_exp2f(x); }
; template <int MODE> DI void attn_h1(AttnCtx& c, const bf16x8 (&q)[8], f32x16 (&o)[4], f32x16& s0, f32x16& s1, ldsp lds, int kbuf, int bbuf, int tj, int lane) {
;     ...
;                     for (int e = 0; e < 16; ++e) {
;                         const float d0 = dbase - (float)(PS * (8 * (e >> 2) + (e & 3))), d1 = d0 - (float)(PS * 32);
;                         bool v0 = d0 >= 0.f, v1 = d1 >= 0.f;
;                         if (MODE == MD_WIN) { v0 = v0 && d0 < 512.f; v1 = v1 && d1 < 512.f; }
;                         if (MODE == MD_SEL) { v0 = v0 && selbit; v1 = v1 && selbit; }
;                         s0[e] = v0 ? s0[e] - c.slope2 * d0 : NINF;
;                         s1[e] = v1 ? s1[e] - c.slope2 * d1 : NINF;
;                     }
; template <int MODE> DI void attn_h2(AttnCtx& c, f32x16 (&o)[4], f32x16& s0, f32x16& s1, ldsp lds, int vbuf, int tj, int lane) {
;     ...
;             if (MODE == MD_CMP2) {
; #pragma unroll
;                 for (int e = 0; e < 16; ++e) { s0[e] = fexp2(s0[e] - c.m) * c.l; s1[e] = fexp2(s1[e] - c.m) * c.l; }
;                 LAS float* impg = (LAS float*)(lds + A_IMPG) + c.qi * 128; LAS float* imp3 = (LAS float*)(lds + A_IMP3) + c.qi * 128;
; #pragma unroll
;                 for (int kb = 0; kb < 2; ++kb)
; #pragma unroll
;                     for (int g4 = 0; g4 < 4; ++g4) {
;                         float G, p3;
;                         if (kb == 0) { G = (s0[4 * g4] + s0[4 * g4 + 1]) + (s0[4 * g4 + 2] + s0[4 * g4 + 3]); p3 = s0[4 * g4 + 3]; }
;                         else { G = (s1[4 * g4] + s1[4 * g4 + 1]) + (s1[4 * g4 + 2] + s1[4 * g4 + 3]); p3 = s1[4 * g4 + 3]; }
;                         G += shx(G, 1, lane); G += shx(G, 2, lane); p3 += shx(p3, 1, lane); p3 += shx(p3, 2, lane);
;                         const int n4 = tj * 16 + kb * 8 + 2 * g4 + h;
;                         if ((lane & 3) == 0) { impg[n4] = G; if (n4 + 1 < 128) imp3[n4 + 1] = p3; }
;                     }
.LBB0_665:
	s_or_b64 exec, exec, s[8:9]
	v_add_f32_e32 v187, 0xc3800000, v179
	v_fma_f32 v90, -v146, v187, v90
	v_cmp_le_f32_e32 vcc, 0, v187
	s_waitcnt lgkmcnt(0)
	v_add_f32_e32 v190, 0xc3880000, v179
	v_fma_f32 v91, -v146, v190, v91
	v_cndmask_b32_e32 v90, v230, v90, vcc
	v_cmp_le_f32_e32 vcc, 0, v190
	v_add_f32_e32 v209, 0xc3900000, v179
	v_fma_f32 v92, -v146, v209, v92
	v_cndmask_b32_e32 v91, v230, v91, vcc
	v_cmp_le_f32_e32 vcc, 0, v209
	v_add_f32_e32 v210, 0xc3980000, v179
	v_fma_f32 v93, -v146, v210, v93
	v_cndmask_b32_e32 v92, v230, v92, vcc
	v_cmp_le_f32_e32 vcc, 0, v210
	v_sub_f32_e32 v90, v90, v155
	v_sub_f32_e32 v91, v91, v155
	v_cndmask_b32_e32 v93, v230, v93, vcc
	v_sub_f32_e32 v92, v92, v155
	v_sub_f32_e32 v93, v93, v155
	v_exp_f32_e32 v90, v90
	v_exp_f32_e32 v91, v91
	v_exp_f32_e32 v92, v92
	v_exp_f32_e32 v93, v93
	v_pk_mul_f32 v[90:91], v[158:159], v[90:91]
	s_nop 0
	v_add_f32_e32 v212, v90, v91
	v_pk_mul_f32 v[92:93], v[158:159], v[92:93]
	s_nop 1
	v_mov_b32_dpp v213, v93 quad_perm:[1,0,3,2] row_mask:0xf bank_mask:0xf
	v_add_f32_e32 v211, v92, v93
	v_add_f32_e32 v211, v212, v211
	s_nop 1
	v_mov_b32_dpp v212, v211 quad_perm:[1,0,3,2] row_mask:0xf bank_mask:0xf
	s_waitcnt lgkmcnt(0)
	v_add_f32_e32 v213, v93, v213
	s_nop 1
	v_mov_b32_dpp v214, v213 quad_perm:[2,3,0,1] row_mask:0xf bank_mask:0xf
	s_waitcnt lgkmcnt(0)
	v_add_f32_e32 v211, v211, v212
	s_nop 1
	v_mov_b32_dpp v212, v211 quad_perm:[2,3,0,1] row_mask:0xf bank_mask:0xf
	s_and_saveexec_b64 s[8:9], s[46:47]
	s_cbranch_execz .LBB0_667
	v_add_u32_e32 v216, 0x119d0, v178
	s_waitcnt lgkmcnt(0)
	v_add_f32_e32 v211, v211, v212
	v_add_u32_e32 v215, 0x199d4, v178
	v_add_f32_e32 v212, v213, v214
	ds_write_b32 v216, v211
	ds_write_b32 v215, v212
.LBB0_667:
	s_or_b64 exec, exec, s[8:9]
	v_add_f32_e32 v211, 0xc3c00000, v179
	v_fma_f32 v94, -v146, v211, v94
	v_cmp_le_f32_e32 vcc, 0, v211
	s_waitcnt lgkmcnt(0)
	v_add_f32_e32 v212, 0xc3c80000, v179
	v_fma_f32 v95, -v146, v212, v95
	v_cndmask_b32_e32 v94, v230, v94, vcc
	v_cmp_le_f32_e32 vcc, 0, v212
	v_add_f32_e32 v213, 0xc3d00000, v179
	v_fma_f32 v96, -v146, v213, v96
	v_cndmask_b32_e32 v95, v230, v95, vcc
	v_cmp_le_f32_e32 vcc, 0, v213
	v_add_f32_e32 v214, 0xc3d80000, v179
	v_fma_f32 v97, -v146, v214, v97
	v_cndmask_b32_e32 v96, v230, v96, vcc
	v_cmp_le_f32_e32 vcc, 0, v214
	v_sub_f32_e32 v94, v94, v155
	v_sub_f32_e32 v95, v95, v155
	v_cndmask_b32_e32 v97, v230, v97, vcc
	v_sub_f32_e32 v96, v96, v155
	v_sub_f32_e32 v97, v97, v155
	v_exp_f32_e32 v94, v94
	v_exp_f32_e32 v95, v95
	v_exp_f32_e32 v96, v96
	v_exp_f32_e32 v97, v97
	v_pk_mul_f32 v[94:95], v[158:159], v[94:95]
	s_nop 0
	v_add_f32_e32 v216, v94, v95
	v_pk_mul_f32 v[96:97], v[158:159], v[96:97]
	s_nop 1
	v_mov_b32_dpp v217, v97 quad_perm:[1,0,3,2] row_mask:0xf bank_mask:0xf
	v_add_f32_e32 v215, v96, v97
	v_add_f32_e32 v215, v216, v215
	s_nop 1
	v_mov_b32_dpp v216, v215 quad_perm:[1,0,3,2] row_mask:0xf bank_mask:0xf
	s_waitcnt lgkmcnt(0)
	v_add_f32_e32 v217, v97, v217
	s_nop 1
	v_mov_b32_dpp v218, v217 quad_perm:[2,3,0,1] row_mask:0xf bank_mask:0xf
	s_waitcnt lgkmcnt(0)
	v_add_f32_e32 v215, v215, v216
	s_nop 1
	v_mov_b32_dpp v216, v215 quad_perm:[2,3,0,1] row_mask:0xf bank_mask:0xf
	s_and_saveexec_b64 s[8:9], s[46:47]
	s_cbranch_execz .LBB0_669
	v_add_u32_e32 v220, 0x119d8, v178
	s_waitcnt lgkmcnt(0)
	v_add_f32_e32 v215, v215, v216
	v_add_u32_e32 v219, 0x199dc, v178
	v_add_f32_e32 v216, v217, v218
	ds_write_b32 v220, v215
	ds_write_b32 v219, v216
.LBB0_669:
	s_or_b64 exec, exec, s[8:9]
	v_add_f32_e32 v179, 0xc4000000, v179
	v_fma_f32 v66, -v146, v179, v66
	v_cmp_le_f32_e32 vcc, 0, v179
	v_add_f32_e32 v179, 0xc4000000, v180
	v_fma_f32 v67, -v146, v179, v67
	v_cndmask_b32_e32 v66, v230, v66, vcc
	v_cmp_le_f32_e32 vcc, 0, v179
	v_add_f32_e32 v179, 0xc4000000, v181
	v_fma_f32 v68, -v146, v179, v68
	v_cndmask_b32_e32 v67, v230, v67, vcc
	v_cmp_le_f32_e32 vcc, 0, v179
	v_add_f32_e32 v179, 0xc4000000, v182
	v_fma_f32 v69, -v146, v179, v69
	v_cndmask_b32_e32 v68, v230, v68, vcc
	v_cmp_le_f32_e32 vcc, 0, v179
	v_sub_f32_e32 v66, v66, v155
	v_sub_f32_e32 v67, v67, v155
	v_cndmask_b32_e32 v69, v230, v69, vcc
	v_sub_f32_e32 v68, v68, v155
	v_sub_f32_e32 v69, v69, v155
	v_exp_f32_e32 v66, v66
	v_exp_f32_e32 v67, v67
	v_exp_f32_e32 v68, v68
	v_exp_f32_e32 v69, v69
	v_pk_mul_f32 v[66:67], v[158:159], v[66:67]
	s_nop 0
	v_add_f32_e32 v180, v66, v67
	v_pk_mul_f32 v[68:69], v[158:159], v[68:69]
	s_nop 1
	v_mov_b32_dpp v181, v69 quad_perm:[1,0,3,2] row_mask:0xf bank_mask:0xf
	v_add_f32_e32 v179, v68, v69
	v_add_f32_e32 v179, v180, v179
	s_nop 1
	v_mov_b32_dpp v180, v179 quad_perm:[1,0,3,2] row_mask:0xf bank_mask:0xf
	s_waitcnt lgkmcnt(0)
	v_add_f32_e32 v181, v69, v181
	s_nop 1
	v_mov_b32_dpp v182, v181 quad_perm:[2,3,0,1] row_mask:0xf bank_mask:0xf
	s_waitcnt lgkmcnt(0)
	v_add_f32_e32 v179, v179, v180
	s_nop 1
	v_mov_b32_dpp v180, v179 quad_perm:[2,3,0,1] row_mask:0xf bank_mask:0xf
	s_and_saveexec_b64 s[8:9], s[46:47]
	s_cbranch_execz .LBB0_671
	v_add_u32_e32 v216, 0x119e0, v178
	s_waitcnt lgkmcnt(0)
	v_add_f32_e32 v179, v179, v180
	v_add_u32_e32 v215, 0x199e4, v178
	v_add_f32_e32 v180, v181, v182
	ds_write_b32 v216, v179
	ds_write_b32 v215, v180
; #define LAS __attribute__((address_space(3)))
; DI float shx(float v, int m, int lane) { return __builtin_bit_cast(float, __builtin_amdgcn_ds_bpermute((lane ^ m) << 2, __builtin_bit_cast(int, v))); }
; DI float fexp2(float x) { return __builtin_amdgcn_exp2f(x); }
; template <int MODE> DI void attn_h1(AttnCtx& c, const bf16x8 (&q)[8], f32x16 (&o)[4], f32x16& s0, f32x16& s1, ldsp lds, int kbuf, int bbuf, int tj, int lane) {
;     ...
;                 if (needmask) {
; #pragma unroll
;                     for (int e = 0; e < 16; ++e) {
;                         const float d0 = dbase - (float)(PS * (8 * (e >> 2) + (e & 3))), d1 = d0 - (float)(PS * 32);
;                         bool v0 = d0 >= 0.f, v1 = d1 >= 0.f;
;                         if (MODE == MD_WIN) { v0 = v0 && d0 < 512.f; v1 = v1 && d1 < 512.f; }
;                         if (MODE == MD_SEL) { v0 = v0 && selbit; v1 = v1 && selbit; }
;                         s0[e] = v0 ? s0[e] - c.slope2 * d0 : NINF;
;                         s1[e] = v1 ? s1[e] - c.slope2 * d1 : NINF;
;                     }
; template <int MODE> DI void attn_h2(AttnCtx& c, f32x16 (&o)[4], f32x16& s0, f32x16& s1, ldsp lds, int vbuf, int tj, int lane) {
;     ...
;             if (MODE == MD_CMP2) {
; #pragma unroll
;                 for (int e = 0; e < 16; ++e) { s0[e] = fexp2(s0[e] - c.m) * c.l; s1[e] = fexp2(s1[e] - c.m) * c.l; }
;                 LAS float* impg = (LAS float*)(lds + A_IMPG) + c.qi * 128; LAS float* imp3 = (LAS float*)(lds + A_IMP3) + c.qi * 128;
; #pragma unroll
;                 for (int kb = 0; kb < 2; ++kb)
; #pragma unroll
;                     for (int g4 = 0; g4 < 4; ++g4) {
;                         float G, p3;
;                         if (kb == 0) { G = (s0[4 * g4] + s0[4 * g4 + 1]) + (s0[4 * g4 + 2] + s0[4 * g4 + 3]); p3 = s0[4 * g4 + 3]; }
;                         else { G = (s1[4 * g4] + s1[4 * g4 + 1]) + (s1[4 * g4 + 2] + s1[4 * g4 + 3]); p3 = s1[4 * g4 + 3]; }
;                         G += shx(G, 1, lane); G += shx(G, 2, lane); p3 += shx(p3, 1, lane); p3 += shx(p3, 2, lane);
;                         const int n4 = tj * 16 + kb * 8 + 2 * g4 + h;
;                         if ((lane & 3) == 0) { impg[n4] = G; if (n4 + 1 < 128) imp3[n4 + 1] = p3; }
;                     }
.LBB0_671:
	s_or_b64 exec, exec, s[8:9]
	v_add_f32_e32 v179, 0xc4000000, v183
	v_fma_f32 v70, -v146, v179, v70
	v_cmp_le_f32_e32 vcc, 0, v179
	v_add_f32_e32 v179, 0xc4000000, v184
	v_fma_f32 v71, -v146, v179, v71
	v_cndmask_b32_e32 v70, v230, v70, vcc
	v_cmp_le_f32_e32 vcc, 0, v179
	v_add_f32_e32 v179, 0xc4000000, v185
	v_fma_f32 v72, -v146, v179, v72
	v_cndmask_b32_e32 v71, v230, v71, vcc
	v_cmp_le_f32_e32 vcc, 0, v179
	v_add_f32_e32 v179, 0xc4000000, v186
	v_fma_f32 v73, -v146, v179, v73
	v_cndmask_b32_e32 v72, v230, v72, vcc
	v_cmp_le_f32_e32 vcc, 0, v179
	v_sub_f32_e32 v70, v70, v155
	v_sub_f32_e32 v71, v71, v155
	v_cndmask_b32_e32 v73, v230, v73, vcc
	v_sub_f32_e32 v72, v72, v155
	v_sub_f32_e32 v73, v73, v155
	v_exp_f32_e32 v70, v70
	v_exp_f32_e32 v71, v71
	v_exp_f32_e32 v72, v72
	v_exp_f32_e32 v73, v73
	v_pk_mul_f32 v[70:71], v[158:159], v[70:71]
	s_waitcnt lgkmcnt(0)
	v_add_f32_e32 v180, v70, v71
	v_pk_mul_f32 v[72:73], v[158:159], v[72:73]
	s_nop 1
	v_mov_b32_dpp v181, v73 quad_perm:[1,0,3,2] row_mask:0xf bank_mask:0xf
	v_add_f32_e32 v179, v72, v73
	v_add_f32_e32 v179, v180, v179
	s_nop 1
	v_mov_b32_dpp v180, v179 quad_perm:[1,0,3,2] row_mask:0xf bank_mask:0xf
	s_waitcnt lgkmcnt(0)
	v_add_f32_e32 v181, v73, v181
	s_nop 1
	v_mov_b32_dpp v182, v181 quad_perm:[2,3,0,1] row_mask:0xf bank_mask:0xf
	s_waitcnt lgkmcnt(0)
	v_add_f32_e32 v179, v179, v180
	s_nop 1
	v_mov_b32_dpp v180, v179 quad_perm:[2,3,0,1] row_mask:0xf bank_mask:0xf
	s_and_saveexec_b64 s[8:9], s[46:47]
	s_cbranch_execz .LBB0_673
	v_add_u32_e32 v184, 0x119e8, v178
	s_waitcnt lgkmcnt(0)
	v_add_f32_e32 v179, v179, v180
	v_add_u32_e32 v183, 0x199ec, v178
	v_add_f32_e32 v180, v181, v182
	ds_write_b32 v184, v179
	ds_write_b32 v183, v180
.LBB0_673:
	s_or_b64 exec, exec, s[8:9]
	v_add_f32_e32 v179, 0xc4000000, v187
	v_fma_f32 v74, -v146, v179, v74
	v_cmp_le_f32_e32 vcc, 0, v179
	v_add_f32_e32 v179, 0xc4000000, v190
	v_fma_f32 v75, -v146, v179, v75
	v_cndmask_b32_e32 v74, v230, v74, vcc
	v_cmp_le_f32_e32 vcc, 0, v179
	v_add_f32_e32 v179, 0xc4000000, v209
	v_fma_f32 v76, -v146, v179, v76
	v_cndmask_b32_e32 v75, v230, v75, vcc
	v_cmp_le_f32_e32 vcc, 0, v179
	v_add_f32_e32 v179, 0xc4000000, v210
	v_fma_f32 v77, -v146, v179, v77
	v_cndmask_b32_e32 v76, v230, v76, vcc
	v_cmp_le_f32_e32 vcc, 0, v179
	v_sub_f32_e32 v74, v74, v155
	v_sub_f32_e32 v75, v75, v155
	v_cndmask_b32_e32 v77, v230, v77, vcc
	v_sub_f32_e32 v76, v76, v155
	v_sub_f32_e32 v77, v77, v155
	v_exp_f32_e32 v74, v74
	v_exp_f32_e32 v75, v75
	v_exp_f32_e32 v76, v76
	v_exp_f32_e32 v77, v77
	v_pk_mul_f32 v[74:75], v[158:159], v[74:75]
	s_waitcnt lgkmcnt(0)
	v_add_f32_e32 v180, v74, v75
	v_pk_mul_f32 v[76:77], v[158:159], v[76:77]
	s_nop 1
	v_mov_b32_dpp v181, v77 quad_perm:[1,0,3,2] row_mask:0xf bank_mask:0xf
	v_add_f32_e32 v179, v76, v77
	v_add_f32_e32 v179, v180, v179
	s_nop 1
	v_mov_b32_dpp v180, v179 quad_perm:[1,0,3,2] row_mask:0xf bank_mask:0xf
	s_waitcnt lgkmcnt(0)
	v_add_f32_e32 v181, v77, v181
	s_nop 1
	v_mov_b32_dpp v182, v181 quad_perm:[2,3,0,1] row_mask:0xf bank_mask:0xf
	s_waitcnt lgkmcnt(0)
	v_add_f32_e32 v179, v179, v180
	s_nop 1
	v_mov_b32_dpp v180, v179 quad_perm:[2,3,0,1] row_mask:0xf bank_mask:0xf
	s_and_saveexec_b64 s[8:9], s[46:47]
	s_cbranch_execz .LBB0_675
	v_add_u32_e32 v184, 0x119f0, v178
	s_waitcnt lgkmcnt(0)
	v_add_f32_e32 v179, v179, v180
	v_add_u32_e32 v183, 0x199f4, v178
	v_add_f32_e32 v180, v181, v182
	ds_write_b32 v184, v179
	ds_write_b32 v183, v180
; #define LAS __attribute__((address_space(3)))
; DI float fexp2(float x) { return __builtin_amdgcn_exp2f(x); }
; template <int MODE> DI void attn_h2(AttnCtx& c, f32x16 (&o)[4], f32x16& s0, f32x16& s1, ldsp lds, int vbuf, int tj, int lane) {
;     ...
;             if (MODE == MD_CMP2) {
; #pragma unroll
;                 for (int e = 0; e < 16; ++e) { s0[e] = fexp2(s0[e] - c.m) * c.l; s1[e] = fexp2(s1[e] - c.m) * c.l; }
;                 LAS float* impg = (LAS float*)(lds + A_IMPG) + c.qi * 128; LAS float* imp3 = (LAS float*)(lds + A_IMP3) + c.qi * 128;
; #pragma unroll
;                 for (int kb = 0; kb < 2; ++kb)
; #pragma unroll
;                     for (int g4 = 0; g4 < 4; ++g4) {
;                         float G, p3;
;                         if (kb == 0) { G = (s0[4 * g4] + s0[4 * g4 + 1]) + (s0[4 * g4 + 2] + s0[4 * g4 + 3]); p3 = s0[4 * g4 + 3]; }
;                         else { G = (s1[4 * g4] + s1[4 * g4 + 1]) + (s1[4 * g4 + 2] + s1[4 * g4 + 3]); p3 = s1[4 * g4 + 3]; }
;                         G += shx(G, 1, lane); G += shx(G, 2, lane); p3 += shx(p3, 1, lane); p3 += shx(p3, 2, lane);
;                         const int n4 = tj * 16 + kb * 8 + 2 * g4 + h;
;                         if ((lane & 3) == 0) { impg[n4] = G; if (n4 + 1 < 128) imp3[n4 + 1] = p3; }
;                     }
;     ...
;             if (MODE != MD_CMP1) {
;                 ldsp vl = lds + vbuf + r32 * VPITCH + 16 * h;
; #pragma unroll
;                 for (int kb = 0; kb < 2; ++kb)
; #pragma unroll
;                     for (int s2 = 0; s2 < 2; ++s2) {
;                         u32x4 pw;
;                         if (kb == 0) { pw.x = pk2(s0[8 * s2], s0[8 * s2 + 1]); pw.y = pk2(s0[8 * s2 + 2], s0[8 * s2 + 3]); pw.z = pk2(s0[8 * s2 + 4], s0[8 * s2 + 5]); pw.w = pk2(s0[8 * s2 + 6], s0[8 * s2 + 7]); }
;                         else { pw.x = pk2(s1[8 * s2], s1[8 * s2 + 1]); pw.y = pk2(s1[8 * s2 + 2], s1[8 * s2 + 3]); pw.z = pk2(s1[8 * s2 + 4], s1[8 * s2 + 5]); pw.w = pk2(s1[8 * s2 + 6], s1[8 * s2 + 7]); }
;                         const bf16x8 pf = __builtin_bit_cast(bf16x8, pw);
; #pragma unroll
;                         for (int db = 0; db < 4; ++db) {
;                             const bf16x8 vf = *(const LAS bf16x8*)(vl + db * 32 * VPITCH + (kb * 2 + s2) * 32);
;                             o[db] = MFMA32(vf, pf, o[db]);
;                         }
;                     }
;             }
.LBB0_675:
	s_or_b64 exec, exec, s[8:9]
	v_add_f32_e32 v179, 0xc4000000, v211
	v_fma_f32 v78, -v146, v179, v78
	v_cmp_le_f32_e32 vcc, 0, v179
	v_add_f32_e32 v179, 0xc4000000, v212
	v_fma_f32 v79, -v146, v179, v79
	v_cndmask_b32_e32 v78, v230, v78, vcc
	v_cmp_le_f32_e32 vcc, 0, v179
	v_add_f32_e32 v179, 0xc4000000, v213
	v_fma_f32 v80, -v146, v179, v80
	v_cndmask_b32_e32 v79, v230, v79, vcc
	v_cmp_le_f32_e32 vcc, 0, v179
	v_add_f32_e32 v179, 0xc4000000, v214
	v_fma_f32 v81, -v146, v179, v81
	v_cndmask_b32_e32 v80, v230, v80, vcc
	v_cmp_le_f32_e32 vcc, 0, v179
	v_sub_f32_e32 v78, v78, v155
	v_sub_f32_e32 v79, v79, v155
	v_cndmask_b32_e32 v81, v230, v81, vcc
	v_sub_f32_e32 v80, v80, v155
	v_sub_f32_e32 v81, v81, v155
	v_exp_f32_e32 v78, v78
	v_exp_f32_e32 v79, v79
	v_exp_f32_e32 v80, v80
	v_exp_f32_e32 v81, v81
	v_pk_mul_f32 v[78:79], v[158:159], v[78:79]
	s_waitcnt lgkmcnt(0)
	v_add_f32_e32 v180, v78, v79
	v_pk_mul_f32 v[80:81], v[158:159], v[80:81]
	s_nop 1
	v_mov_b32_dpp v181, v81 quad_perm:[1,0,3,2] row_mask:0xf bank_mask:0xf
	v_add_f32_e32 v179, v80, v81
	v_add_f32_e32 v179, v180, v179
	s_nop 1
	v_mov_b32_dpp v180, v179 quad_perm:[1,0,3,2] row_mask:0xf bank_mask:0xf
	s_waitcnt lgkmcnt(0)
	v_add_f32_e32 v181, v81, v181
	s_nop 1
	v_mov_b32_dpp v182, v181 quad_perm:[2,3,0,1] row_mask:0xf bank_mask:0xf
	s_waitcnt lgkmcnt(0)
	v_add_f32_e32 v179, v179, v180
	s_nop 1
	v_mov_b32_dpp v180, v179 quad_perm:[2,3,0,1] row_mask:0xf bank_mask:0xf
	s_and_saveexec_b64 s[8:9], s[46:47]
	s_cbranch_execz .LBB0_677
	v_add_u32_e32 v183, 0x199fc, v178
	v_add_u32_e32 v178, 0x119f8, v178
	s_waitcnt lgkmcnt(0)
	v_add_f32_e32 v179, v179, v180
	v_add_f32_e32 v180, v181, v182
	ds_write_b32 v178, v179
	ds_write_b32 v183, v180
.LBB0_677:
	s_or_b64 exec, exec, s[8:9]
	s_mul_i32 s8, s10, 0x4800
	s_waitcnt lgkmcnt(0)
	v_add_u32_e32 v182, s8, v0
	v_cvt_pk_bf16_f32 v82, v82, v83
	v_cvt_pk_bf16_f32 v83, v84, v85
	v_cvt_pk_bf16_f32 v84, v86, v87
	v_cvt_pk_bf16_f32 v85, v88, v89
	ds_read_b128 v[86:89], v182 offset:34816
	s_waitcnt lgkmcnt(1)
	ds_read_b128 v[178:181], v182 offset:34848
	s_waitcnt lgkmcnt(1)
	v_mfma_f32_32x32x16_bf16 v[50:65], v[86:89], v[82:85], v[50:65]
	ds_read_b128 v[86:89], v182 offset:39424
	v_cvt_pk_bf16_f32 v66, v66, v67
	v_cvt_pk_bf16_f32 v67, v68, v69
	v_cvt_pk_bf16_f32 v68, v70, v71
	v_cvt_pk_bf16_f32 v69, v72, v73
	ds_read_b128 v[70:73], v182 offset:34880
	s_waitcnt lgkmcnt(1)
	v_mfma_f32_32x32x16_bf16 v[34:49], v[86:89], v[82:85], v[34:49]
	ds_read_b128 v[86:89], v182 offset:44032
	s_waitcnt lgkmcnt(0)
	v_mfma_f32_32x32x16_bf16 v[18:33], v[86:89], v[82:85], v[18:33]
	ds_read_b128 v[86:89], v182 offset:48640
	s_waitcnt lgkmcnt(0)
	v_mfma_f32_32x32x16_bf16 v[2:17], v[86:89], v[82:85], v[2:17]
	v_cvt_pk_bf16_f32 v82, v90, v91
	v_cvt_pk_bf16_f32 v83, v92, v93
	v_cvt_pk_bf16_f32 v84, v94, v95
	v_cvt_pk_bf16_f32 v85, v96, v97
	ds_read_b128 v[86:89], v182 offset:39456
	s_nop 0
	v_mfma_f32_32x32x16_bf16 v[50:65], v[178:181], v[82:85], v[50:65]
	v_mfma_f32_32x32x16_bf16 v[50:65], v[70:73], v[66:69], v[50:65]
	ds_read_b128 v[70:73], v182 offset:39488
	s_waitcnt lgkmcnt(1)
	v_mfma_f32_32x32x16_bf16 v[34:49], v[86:89], v[82:85], v[34:49]
	ds_read_b128 v[86:89], v182 offset:44064
	s_waitcnt lgkmcnt(1)
	v_mfma_f32_32x32x16_bf16 v[34:49], v[70:73], v[66:69], v[34:49]
	ds_read_b128 v[70:73], v182 offset:44096
	s_waitcnt lgkmcnt(1)
	v_mfma_f32_32x32x16_bf16 v[18:33], v[86:89], v[82:85], v[18:33]
	ds_read_b128 v[86:89], v182 offset:48672
	s_waitcnt lgkmcnt(1)
	v_mfma_f32_32x32x16_bf16 v[18:33], v[70:73], v[66:69], v[18:33]
	ds_read_b128 v[70:73], v182 offset:48704
	s_waitcnt lgkmcnt(1)
	v_mfma_f32_32x32x16_bf16 v[2:17], v[86:89], v[82:85], v[2:17]
	s_waitcnt lgkmcnt(0)
	v_mfma_f32_32x32x16_bf16 v[2:17], v[70:73], v[66:69], v[2:17]
	ds_read_b128 v[70:73], v182 offset:34912
	v_cvt_pk_bf16_f32 v66, v74, v75
	v_cvt_pk_bf16_f32 v67, v76, v77
	v_cvt_pk_bf16_f32 v68, v78, v79
	v_cvt_pk_bf16_f32 v69, v80, v81
	s_waitcnt lgkmcnt(0)
	s_nop 0
	v_mfma_f32_32x32x16_bf16 v[50:65], v[70:73], v[66:69], v[50:65]
	ds_read_b128 v[70:73], v182 offset:39520
	s_waitcnt lgkmcnt(0)
	v_mfma_f32_32x32x16_bf16 v[34:49], v[70:73], v[66:69], v[34:49]
	ds_read_b128 v[70:73], v182 offset:44128
	s_waitcnt lgkmcnt(0)
	v_mfma_f32_32x32x16_bf16 v[18:33], v[70:73], v[66:69], v[18:33]
	ds_read_b128 v[70:73], v182 offset:48736
	s_waitcnt lgkmcnt(0)
	v_mfma_f32_32x32x16_bf16 v[2:17], v[70:73], v[66:69], v[2:17]
	s_andn2_b64 vcc, exec, s[6:7]
	s_xor_b32 s10, s10, 1
	s_cbranch_vccnz .LBB0_659
